# v049 + grid barrier leader no longer waits for its release atomics before the closing barrier
# baseline (speedup 1.0000x reference)
; __device__ __forceinline__ void xcd_barrier(const XcdBarrier& b) {
;     asm volatile("s_waitcnt vmcnt(0)" ::: "memory");
;     __syncthreads();
;     if (threadIdx.x == 0) {
;         unsigned* bar = b.bar;
;         __builtin_amdgcn_s_waitcnt(0);
;         __builtin_amdgcn_fence(__ATOMIC_ACQUIRE, "agent");
;         asm volatile("s_waitcnt vmcnt(0)" ::: "memory");
;         unsigned nloc = b.st[0], nx = b.st[1];
;         if (nloc == 0u) { xcd_barrier_complete(bar, b.x, nloc, nx); b.st[0] = nloc; b.st[1] = nx; }
;         const unsigned old = xb_add(&bar[XB_XSUB(b.x)], 1u);
;         const unsigned gen = old / nloc;
;         if (old + 1u == (gen + 1u) * nloc) {
;             __builtin_amdgcn_fence(__ATOMIC_RELEASE, "agent");
;             asm volatile("s_waitcnt vmcnt(0)" ::: "memory");
;             const unsigned og = xb_add(&bar[XB_TOP], 1u);
;             const unsigned tg = og / nx;
;             if (og + 1u == (tg + 1u) * nx) xb_add(&bar[XB_TOPGEN], 1u);
;             else XB_SPIN(xb_ld(&bar[XB_TOPGEN]) == tg, bar);
;             asm volatile("" ::: "memory");
;             xb_add(&bar[XB_XGEN(b.x)], 1u);
;             asm volatile("s_waitcnt vmcnt(0)" ::: "memory");
;         } else {
;             XB_SPIN(xb_ld(&bar[XB_XGEN(b.x)]) == gen, bar);
;             asm volatile("" ::: "memory");
;             asm volatile("s_waitcnt vmcnt(0)" ::: "memory");
;         }
;     }
;     __syncthreads();
; }
; __global__ void __launch_bounds__(512, 2) fwd_mega(Args a) {
;     ...
;             for (int m0 = gw; m0 < M; m0 += 2 * NGW) {
;                 const int m1 = m0 + NGW; const bool has1 = m1 < M; const int m1c = has1 ? m1 : m0;
;                 const f32x4* xr0 = (const f32x4*)(xin + (size_t)m0 * D) + lane; const f32x4* xr1 = (const f32x4*)(xin + (size_t)m1c * D) + lane;
;                 f32x4 v0[4], v1[4]; float ss0 = 0.f, ss1 = 0.f;
; #pragma unroll
;                 for (int j = 0; j < 4; ++j) { v0[j] = xr0[64 * j]; v1[j] = xr1[64 * j]; }
; #pragma unroll
;                 for (int j = 0; j < 4; ++j) { ss0 += (v0[j].x * v0[j].x + v0[j].y * v0[j].y) + (v0[j].z * v0[j].z + v0[j].w * v0[j].w); ss1 += (v1[j].x * v1[j].x + v1[j].y * v1[j].y) + (v1[j].z * v1[j].z + v1[j].w * v1[j].w); }
;                 const float rstd0 = rsqrtf(wave_sum(ss0) * (1.f / D) + 1e-6f), rstd1 = rsqrtf(wave_sum(ss1) * (1.f / D) + 1e-6f);
.LBB0_98:
	s_or_b64 exec, exec, s[10:11]
.LBB0_99:
	s_or_b64 exec, exec, s[4:5]
	s_cmpk_gt_i32 s22, 0x3fff
	s_waitcnt lgkmcnt(0)
	v_mbcnt_lo_u32_b32 v1, -1, 0
	s_barrier
	s_cbranch_scc1 .LBB0_110
	v_mbcnt_hi_u32_b32 v2, -1, v1
	v_and_b32_e32 v3, 64, v2
	v_add_u32_e32 v3, 64, v3
	v_xor_b32_e32 v4, 1, v2
	v_cmp_lt_i32_e32 vcc, v4, v3
	s_mov_b64 s[6:7], s[26:27]
	v_readlane_b32 s4, v247, 0
	v_readlane_b32 s5, v247, 1
	v_readlane_b32 s8, v247, 10
	v_readlane_b32 s9, v247, 11
	s_nop 4
	v_cndmask_b32_e32 v4, v2, v4, vcc
	v_lshlrev_b32_e32 v57, 2, v4
	v_xor_b32_e32 v4, 2, v2
	v_cmp_lt_i32_e32 vcc, v4, v3
	v_mov_b32_e32 v173, 0
	s_ashr_i32 s23, s22, 31
	v_cndmask_b32_e32 v4, v2, v4, vcc
	v_lshlrev_b32_e32 v66, 2, v4
	v_xor_b32_e32 v4, 4, v2
	v_cmp_lt_i32_e32 vcc, v4, v3
	s_waitcnt lgkmcnt(0)
	v_lshl_add_u64 v[50:51], s[8:9], 0, v[172:173]
	s_lshl_b32 s8, s3, 4
	v_cndmask_b32_e32 v4, v2, v4, vcc
	v_lshlrev_b32_e32 v67, 2, v4
	v_xor_b32_e32 v4, 8, v2
	v_cmp_lt_i32_e32 vcc, v4, v3
	s_lshl_b64 s[10:11], s[22:23], 12
	v_lshl_add_u64 v[46:47], s[4:5], 0, v[172:173]
	v_cndmask_b32_e32 v4, v2, v4, vcc
	v_lshlrev_b32_e32 v68, 2, v4
	v_xor_b32_e32 v4, 16, v2
	v_cmp_lt_i32_e32 vcc, v4, v3
	s_add_u32 s4, s4, s10
	s_addc_u32 s5, s5, s11
	v_cndmask_b32_e32 v4, v2, v4, vcc
	v_lshlrev_b32_e32 v69, 2, v4
	v_xor_b32_e32 v4, 32, v2
	v_cmp_lt_i32_e32 vcc, v4, v3
	s_ashr_i32 s9, s8, 31
	v_mov_b32_e32 v3, v173
	v_cndmask_b32_e32 v2, v2, v4, vcc
	v_lshlrev_b32_e32 v70, 2, v2
	v_lshlrev_b32_e32 v2, 3, v114
	v_lshl_add_u64 v[52:53], s[4:5], 0, v[172:173]
	s_lshl_b64 s[10:11], s[8:9], 12
	s_lshl_b64 s[4:5], s[22:23], 11
	v_lshl_add_u64 v[4:5], s[6:7], 0, v[2:3]
	s_mov_b64 s[12:13], 0x2b00000
	s_add_u32 s4, s6, s4
	v_lshl_add_u64 v[48:49], v[4:5], 0, s[12:13]
	v_lshlrev_b32_e32 v4, 2, v114
	s_addc_u32 s5, s7, s5
	v_or_b32_e32 v6, 0x100, v4
	v_or_b32_e32 v8, 0x200, v4
	v_or_b32_e32 v10, 0x300, v4
	v_lshl_add_u64 v[2:3], s[4:5], 0, v[2:3]
	v_lshl_add_u64 v[54:55], v[2:3], 0, s[12:13]
	s_lshl_b64 s[12:13], s[8:9], 11
	s_mov_b32 s14, 0x3a800000
	v_mov_b32_e32 v56, 0x358637bd
	s_mov_b32 s9, 0x800000
	v_lshlrev_b32_e32 v58, 2, v4
	v_mov_b32_e32 v59, v173
	v_lshlrev_b32_e32 v71, 2, v6
	v_lshlrev_b32_e32 v72, 2, v8
	v_lshlrev_b32_e32 v73, 2, v10
	s_mov_b32 s15, s22
	s_branch .LBB0_102

;     __host__ __device__ bool next(int i, Unit& u) const { Unit b; if (!base.next(i >> 1, b)) return false; u.pm = b.pm; u.pn = b.pn + 4 * (i & 1); return true; }
; __device__ __forceinline__ unsigned xb_ld(unsigned* p)              { return __hip_atomic_load(p, __ATOMIC_RELAXED, __HIP_MEMORY_SCOPE_AGENT); }
; __device__ __forceinline__ unsigned xb_add(unsigned* p, unsigned v) { return __hip_atomic_fetch_add(p, v, __ATOMIC_RELAXED, __HIP_MEMORY_SCOPE_AGENT); }
;     __host__ __device__ bool next(int i, Unit& u) const {
;         if (G != 256) return base.next(i, u);
;         const int x = c & 7, j = c >> 3;
;         if (j < 8) { if (i >= 6) return false; u.pm = 8 * x + j; u.pn = (i < 5) ? i : 20; return true; }
;         if (i >= 5) return false;
;         const int uidx = (j - 8) + 24 * i; u.pm = 8 * x + (uidx & 7); u.pn = 5 + (uidx >> 3); return true;
;     }
; __device__ __forceinline__ void xcd_barrier(const XcdBarrier& b) {
;     asm volatile("s_waitcnt vmcnt(0)" ::: "memory");
;     __syncthreads();
;     if (threadIdx.x == 0) {
;         unsigned* bar = b.bar;
;         __builtin_amdgcn_s_waitcnt(0);
;         __builtin_amdgcn_fence(__ATOMIC_ACQUIRE, "agent");
;         asm volatile("s_waitcnt vmcnt(0)" ::: "memory");
;         unsigned nloc = b.st[0], nx = b.st[1];
;         if (nloc == 0u) { xcd_barrier_complete(bar, b.x, nloc, nx); b.st[0] = nloc; b.st[1] = nx; }
;         const unsigned old = xb_add(&bar[XB_XSUB(b.x)], 1u);
;         const unsigned gen = old / nloc;
;         if (old + 1u == (gen + 1u) * nloc) {
;             __builtin_amdgcn_fence(__ATOMIC_RELEASE, "agent");
;             asm volatile("s_waitcnt vmcnt(0)" ::: "memory");
;             const unsigned og = xb_add(&bar[XB_TOP], 1u);
;             const unsigned tg = og / nx;
;             if (og + 1u == (tg + 1u) * nx) xb_add(&bar[XB_TOPGEN], 1u);
;             else XB_SPIN(xb_ld(&bar[XB_TOPGEN]) == tg, bar);
;             asm volatile("" ::: "memory");
;             xb_add(&bar[XB_XGEN(b.x)], 1u);
;             asm volatile("s_waitcnt vmcnt(0)" ::: "memory");
;         } else {
;             XB_SPIN(xb_ld(&bar[XB_XGEN(b.x)]) == gen, bar);
;             asm volatile("" ::: "memory");
;             asm volatile("s_waitcnt vmcnt(0)" ::: "memory");
;         }
;     }
;     __syncthreads();
; }
.LBB0_161:
	s_or_b64 exec, exec, s[10:11]
.LBB0_162:
	s_or_b64 exec, exec, s[4:5]
	s_cmpk_lg_i32 s3, 0x100
	s_waitcnt vmcnt(2)
	v_mov_b32_e32 v10, v0
	s_cselect_b64 s[4:5], -1, 0
	s_waitcnt lgkmcnt(0)
	s_barrier
	v_writelane_b32 v246, s4, 8
	s_cmpk_eq_i32 s3, 0x100
	v_readfirstlane_b32 s8, v10
	v_writelane_b32 v246, s5, 9
	s_cbranch_scc1 .LBB0_165
	s_mov_b64 s[4:5], 0
	s_cmpk_gt_i32 s2, 0x53f
	s_mov_b64 s[6:7], 0
	s_cbranch_scc1 .LBB0_166
	s_ashr_i32 s6, s2, 31
	s_lshr_b32 s6, s6, 29
	s_add_i32 s6, s2, s6
	s_ashr_i32 s7, s6, 3
	s_and_b32 s6, s6, -8
	s_sub_i32 s6, s2, s6
	s_cmp_lt_i32 s6, 0
	s_movk_i32 s9, 0xa9
	s_cselect_b32 s9, s9, 0xa8
	s_mul_i32 s6, s9, s6
	s_add_i32 s6, s6, s7
	s_mul_hi_i32 s7, s6, 0x30c30c31
	s_lshr_b32 s9, s7, 31
	s_ashr_i32 s7, s7, 5
	s_add_i32 s7, s7, s9
	s_lshl_b32 s9, s7, 3
	s_mulk_i32 s7, 0xa8
	s_sub_i32 s6, s6, s7
	s_sext_i32_i16 s7, s6
	s_bfe_u32 s7, s7, 0x3001c
	s_add_i32 s7, s6, s7
	s_sext_i32_i16 s10, s7
	s_and_b32 s7, s7, 0xfff8
	s_sub_i32 s6, s6, s7
	s_sext_i32_i16 s6, s6
	s_add_i32 s12, s9, s6
	s_ashr_i32 s16, s10, 3
	s_mov_b64 s[6:7], -1
	s_branch .LBB0_166

; #define LAS __attribute__((address_space(3)))
; __device__ __forceinline__ void attn_unit(LAS unsigned char* lds, bf16* Q, const bf16* Kg, const bf16* Vg, const float* snk, int unit, int tid) {
;     const int lane = tid & 63, wave = tid >> 6, fr = lane & 15, fq = lane >> 4;
;     const int b = unit >> 6, n = (unit >> 1) & 31, h = unit & 1, r0 = b * SEQ + n * 128, hq = 8 * h + wave;
;     const v4u zero4 = {0u, 0u, 0u, 0u};
;     bf16* qbase = Q + (size_t)(r0 + fr) * 1024 + hq * 64;
;     bf16x8_t qf[8][2];
; #pragma unroll
;     for (int mt = 0; mt < 8; ++mt) { qf[mt][0] = *(const bf16x8_t*)(qbase + (size_t)mt * 16 * 1024 + 8 * fq); qf[mt][1] = *(const bf16x8_t*)(qbase + (size_t)mt * 16 * 1024 + 32 + 8 * fq); }
; #pragma unroll
;     for (int i = 0; i < 4; ++i) { const int idx = tid + 512 * i, j = idx >> 3, c = idx & 7, p = n * 128 - 128 + j;
;         v4u w = zero4; if (p >= 0) w = *(const v4u*)(Kg + (size_t)(b * SEQ + p) * 128 + h * 64 + c * 8);
; __device__ __forceinline__ void xcd_barrier(const XcdBarrier& b) {
;     asm volatile("s_waitcnt vmcnt(0)" ::: "memory");
;     __syncthreads();
;     if (threadIdx.x == 0) {
;         unsigned* bar = b.bar;
;         __builtin_amdgcn_s_waitcnt(0);
;         __builtin_amdgcn_fence(__ATOMIC_ACQUIRE, "agent");
;         asm volatile("s_waitcnt vmcnt(0)" ::: "memory");
;         unsigned nloc = b.st[0], nx = b.st[1];
;         if (nloc == 0u) { xcd_barrier_complete(bar, b.x, nloc, nx); b.st[0] = nloc; b.st[1] = nx; }
;         const unsigned old = xb_add(&bar[XB_XSUB(b.x)], 1u);
;         const unsigned gen = old / nloc;
;         if (old + 1u == (gen + 1u) * nloc) {
;             __builtin_amdgcn_fence(__ATOMIC_RELEASE, "agent");
;             asm volatile("s_waitcnt vmcnt(0)" ::: "memory");
;             const unsigned og = xb_add(&bar[XB_TOP], 1u);
;             const unsigned tg = og / nx;
;             if (og + 1u == (tg + 1u) * nx) xb_add(&bar[XB_TOPGEN], 1u);
;             else XB_SPIN(xb_ld(&bar[XB_TOPGEN]) == tg, bar);
;             asm volatile("" ::: "memory");
;             xb_add(&bar[XB_XGEN(b.x)], 1u);
;             asm volatile("s_waitcnt vmcnt(0)" ::: "memory");
;         } else {
;             XB_SPIN(xb_ld(&bar[XB_XGEN(b.x)]) == gen, bar);
;             asm volatile("" ::: "memory");
;             asm volatile("s_waitcnt vmcnt(0)" ::: "memory");
;         }
;     }
;     __syncthreads();
; }
.LBB0_490:
	s_or_b64 exec, exec, s[10:11]
.LBB0_491:
	s_or_b64 exec, exec, s[4:5]
	s_cmpk_lt_i32 s2, 0x200
	s_cselect_b64 s[4:5], -1, 0
	v_mov_b32_e32 v161, v0
	v_writelane_b32 v246, s4, 18
	s_cmpk_gt_i32 s2, 0x1ff
	s_waitcnt lgkmcnt(0)
	s_barrier
	v_writelane_b32 v246, s5, 19
	s_cbranch_scc1 .LBB0_512
	s_mov_b64 s[14:15], s[26:27]
	v_readlane_b32 s42, v247, 22
	v_readlane_b32 s43, v247, 23
	s_nop 4
	v_and_b32_e32 v6, 7, v161
	v_add_u32_e32 v8, 0x200, v161
	v_lshlrev_b32_e32 v170, 3, v6
	v_mul_u32_u24_e32 v10, 0x110, v6
	v_bfe_u32 v15, v161, 4, 2
	v_lshlrev_b32_e32 v4, 4, v6
	s_waitcnt vmcnt(1)
	v_mul_u32_u24_e32 v20, 0x1080, v6
	v_ashrrev_i32_e32 v6, 2, v8
	v_ashrrev_i32_e32 v169, 6, v161
	s_movk_i32 s6, 0x4400
	v_add_u32_e32 v9, 0x400, v161
	v_and_b32_e32 v177, -2, v6
	v_lshlrev_b32_e32 v6, 2, v15
	s_waitcnt lgkmcnt(0)
	s_add_u32 s48, s14, 0x4b00000
	v_and_b32_e32 v3, 63, v161
	v_and_b32_e32 v163, 15, v161
	v_mul_lo_u32 v5, v169, s6
	v_ashrrev_i32_e32 v173, 3, v8
	v_ashrrev_i32_e32 v174, 3, v9
	v_add_u32_e32 v9, 0x600, v161
	v_or_b32_e32 v8, 2, v6
	s_addc_u32 s49, s15, 0
	v_mov_b32_e32 v147, 0
	v_ashrrev_i32_e32 v175, 3, v9
	v_ashrrev_i32_e32 v9, 2, v161
	v_cmp_gt_u32_e64 s[10:11], v8, v163
	v_or_b32_e32 v8, 3, v6
	v_lshlrev_b32_e32 v146, 4, v3
	s_add_u32 s52, s14, 0xf400000
	v_add_u32_e32 v3, 0, v5
	v_lshrrev_b32_e32 v5, 1, v161
	v_bfe_u32 v2, v161, 3, 3
	v_and_b32_e32 v176, -2, v9
	v_cmp_gt_u32_e64 s[12:13], v8, v163
	v_lshl_add_u64 v[8:9], s[14:15], 0, v[146:147]
	s_mov_b64 s[16:17], 0x680000
	s_addc_u32 s53, s15, 0
	v_and_b32_e32 v146, 24, v5
	v_lshlrev_b32_e32 v167, 3, v161
	v_lshlrev_b32_e32 v7, 11, v2
	v_lshlrev_b32_e32 v11, 2, v2
	v_lshlrev_b32_e32 v12, 4, v2
	v_bfe_u32 v2, v161, 3, 1
	v_lshl_add_u64 v[148:149], v[8:9], 0, s[16:17]
	v_lshl_add_u64 v[8:9], s[14:15], 0, v[146:147]
	s_mov_b64 s[16:17], 0x9300000
	s_add_u32 s56, s14, 0x6b00000
	v_mov_b32_e32 v5, v147
	v_and_or_b32 v2, v167, 56, v2
	v_readlane_b32 s28, v247, 14
	v_readlane_b32 s29, v247, 15
	v_readlane_b32 s30, v247, 16
	v_readlane_b32 s31, v247, 17
	v_readlane_b32 s50, v247, 18
	v_readlane_b32 s51, v247, 19
	s_nop 4
	v_lshl_add_u64 v[150:151], v[8:9], 0, s[16:17]
	s_addc_u32 s57, s15, 0
	v_add_u32_e32 v8, 0, v4
	v_lshl_add_u64 v[4:5], s[14:15], 0, v[4:5]
	s_mov_b64 s[14:15], 0x8b00000
	v_mul_u32_u24_e32 v14, 0x110, v2
	v_lshlrev_b32_e32 v2, 3, v15
	v_lshl_add_u64 v[152:153], v[4:5], 0, s[14:15]
	s_mov_b64 s[14:15], 0x8f00000
	v_lshl_add_u32 v9, v15, 4, 0
	v_and_b32_e32 v13, 48, v161
	v_ashrrev_i32_e32 v171, 3, v161
	s_movk_i32 s18, 0x90
	v_add3_u32 v178, v3, v10, v11
	v_lshl_add_u64 v[154:155], v[4:5], 0, s[14:15]
	v_sub_u32_e32 v10, v9, v2
	s_movk_i32 s14, 0x210
	s_movk_i32 s4, 0x80
	v_mul_lo_u32 v16, v171, s18
	v_mul_lo_u32 v17, v173, s18
	v_mul_lo_u32 v18, v174, s18
	v_mul_lo_u32 v19, v175, s18
	v_add_u32_e32 v3, v3, v13
	v_lshl_add_u32 v4, v176, 1, 0
	v_lshl_add_u32 v5, v177, 1, 0
	v_mad_u32_u24 v180, v163, s14, v10
	s_lshl_b32 s14, s2, 2
	v_ashrrev_i32_e32 v165, 7, v161
	v_cmp_gt_i32_e64 s[4:5], s4, v161
	v_and_b32_e32 v168, 64, v161
	v_cmp_gt_u32_e64 s[6:7], v6, v163
	v_cmp_lt_u32_e64 s[8:9], v6, v163
	s_mov_b32 s55, 0
	v_mad_u32_u24 v179, v163, s18, v9
	s_add_i32 s23, s14, 0xfffffc00
	s_lshl_b32 s24, s3, 2
	s_lshl_b32 s25, s2, 6
	s_lshl_b32 s34, s3, 6
	s_movk_i32 s35, 0x1000
	s_movk_i32 s36, 0x2000
	s_movk_i32 s37, 0x3000
	s_movk_i32 s38, 0x4000
	s_mov_b32 s58, 0x3a800000
	s_mov_b32 s39, 0x800000
	v_lshlrev_b32_e32 v181, 1, v7
	s_mov_b32 s40, 0x8000
	s_mov_b32 s41, 0x10000
	s_mov_b32 s44, 0x18000
	s_mov_b32 s45, 0x20000
	s_mov_b32 s46, 0x28000
	s_mov_b32 s47, 0x30000
	s_mov_b32 s59, 0x38000
	v_add_u32_e32 v182, 0, v12
	s_mov_b32 s60, 0xffff0000
	v_add_u32_e32 v183, v3, v14
	v_lshlrev_b32_e32 v146, 1, v2
	v_add_u32_e32 v184, v8, v16
	v_add_u32_e32 v185, v8, v17
	v_add_u32_e32 v186, v8, v18
	v_add_u32_e32 v187, v8, v19
	s_mov_b32 s61, 0xffff
	v_add_u32_e32 v188, v4, v20
	v_add_u32_e32 v189, v5, v20
	s_mov_b32 s62, 0x3fb8aa3b
	v_lshlrev_b32_e32 v156, 1, v6
	v_mbcnt_hi_u32_b32 v190, -1, v1
	v_mov_b32_e32 v191, 0xff800000
	s_mov_b32 s63, s2
	s_branch .LBB0_495

;     __host__ __device__ void init(int M, int N, int G_, int c_) { base.init(M, N, G_, c_); G = G_; c = c_; }
; __device__ __forceinline__ unsigned xb_ld(unsigned* p)              { return __hip_atomic_load(p, __ATOMIC_RELAXED, __HIP_MEMORY_SCOPE_AGENT); }
; __device__ __forceinline__ unsigned xb_add(unsigned* p, unsigned v) { return __hip_atomic_fetch_add(p, v, __ATOMIC_RELAXED, __HIP_MEMORY_SCOPE_AGENT); }
; #define XB_SPIN(cond, bar) do { unsigned _sp = 0; while (cond) { __builtin_amdgcn_s_sleep(1); \
;     if ((++_sp & 255u) == 0u) { if (xb_ld(&(bar)[XB_TMO])) break; if (_sp > XB_SPIN_CAP) { atomicAdd(&(bar)[XB_TMO], 1u); break; } } } } while (0)
;     __host__ __device__ void init(int M, int G_, int c_) { base.init(M, 1024, G_, c_); }
;     __host__ __device__ bool next(int i, Unit& u) const { Unit b; if (!base.next(i >> 1, b)) return false; u.pm = b.pm; u.pn = b.pn + 4 * (i & 1); return true; }
; __device__ __forceinline__ void xcd_barrier(const XcdBarrier& b) {
;     asm volatile("s_waitcnt vmcnt(0)" ::: "memory");
;     __syncthreads();
;     if (threadIdx.x == 0) {
;         unsigned* bar = b.bar;
;         __builtin_amdgcn_s_waitcnt(0);
;         __builtin_amdgcn_fence(__ATOMIC_ACQUIRE, "agent");
;         asm volatile("s_waitcnt vmcnt(0)" ::: "memory");
;         unsigned nloc = b.st[0], nx = b.st[1];
;         if (nloc == 0u) { xcd_barrier_complete(bar, b.x, nloc, nx); b.st[0] = nloc; b.st[1] = nx; }
;         const unsigned old = xb_add(&bar[XB_XSUB(b.x)], 1u);
;         const unsigned gen = old / nloc;
;         if (old + 1u == (gen + 1u) * nloc) {
;             __builtin_amdgcn_fence(__ATOMIC_RELEASE, "agent");
;             asm volatile("s_waitcnt vmcnt(0)" ::: "memory");
;             const unsigned og = xb_add(&bar[XB_TOP], 1u);
;             const unsigned tg = og / nx;
;             if (og + 1u == (tg + 1u) * nx) xb_add(&bar[XB_TOPGEN], 1u);
;             else XB_SPIN(xb_ld(&bar[XB_TOPGEN]) == tg, bar);
;             asm volatile("" ::: "memory");
;             xb_add(&bar[XB_XGEN(b.x)], 1u);
;             asm volatile("s_waitcnt vmcnt(0)" ::: "memory");
;         } else {
;             XB_SPIN(xb_ld(&bar[XB_XGEN(b.x)]) == gen, bar);
;             asm volatile("" ::: "memory");
;             asm volatile("s_waitcnt vmcnt(0)" ::: "memory");
;         }
;     }
;     __syncthreads();
; }
.LBB0_563:
	s_or_b64 exec, exec, s[10:11]
.LBB0_564:
	s_or_b64 exec, exec, s[4:5]
	s_waitcnt lgkmcnt(0)
	s_barrier
	s_mov_b64 s[6:7], s[26:27]
	v_mov_b32_e32 v10, v0
	s_cmpk_lt_i32 s2, 0x100
	s_cselect_b64 s[8:9], -1, 0
	s_cmpk_gt_i32 s2, 0xff
	v_readfirstlane_b32 s20, v10
	s_cbranch_scc1 .LBB0_570
	s_ashr_i32 s4, s2, 31
	s_lshr_b32 s4, s4, 29
	s_add_i32 s10, s2, s4
	s_and_b32 s4, s10, -8
	s_sub_i32 s11, s2, s4
	s_cmp_gt_i32 s11, -1
	s_cbranch_scc0 .LBB0_567
	s_lshl_b32 s12, s11, 5
	s_cbranch_execz .LBB0_568
	s_branch .LBB0_569

;     __host__ __device__ void init(int M, int N, int G_, int c_) { base.init(M, N, G_, c_); G = G_; c = c_; }
;     __host__ __device__ void init(int M, int G_, int c_) { base.init(M, 1024, G_, c_); }
; __device__ __forceinline__ unsigned xb_ld(unsigned* p)              { return __hip_atomic_load(p, __ATOMIC_RELAXED, __HIP_MEMORY_SCOPE_AGENT); }
; __device__ __forceinline__ unsigned xb_add(unsigned* p, unsigned v) { return __hip_atomic_fetch_add(p, v, __ATOMIC_RELAXED, __HIP_MEMORY_SCOPE_AGENT); }
; __device__ __forceinline__ void xcd_barrier(const XcdBarrier& b) {
;     asm volatile("s_waitcnt vmcnt(0)" ::: "memory");
;     __syncthreads();
;     if (threadIdx.x == 0) {
;         unsigned* bar = b.bar;
;         __builtin_amdgcn_s_waitcnt(0);
;         __builtin_amdgcn_fence(__ATOMIC_ACQUIRE, "agent");
;         asm volatile("s_waitcnt vmcnt(0)" ::: "memory");
;         unsigned nloc = b.st[0], nx = b.st[1];
;         if (nloc == 0u) { xcd_barrier_complete(bar, b.x, nloc, nx); b.st[0] = nloc; b.st[1] = nx; }
;         const unsigned old = xb_add(&bar[XB_XSUB(b.x)], 1u);
;         const unsigned gen = old / nloc;
;         if (old + 1u == (gen + 1u) * nloc) {
;             __builtin_amdgcn_fence(__ATOMIC_RELEASE, "agent");
;             asm volatile("s_waitcnt vmcnt(0)" ::: "memory");
;             const unsigned og = xb_add(&bar[XB_TOP], 1u);
;             const unsigned tg = og / nx;
;             if (og + 1u == (tg + 1u) * nx) xb_add(&bar[XB_TOPGEN], 1u);
;             else XB_SPIN(xb_ld(&bar[XB_TOPGEN]) == tg, bar);
;             asm volatile("" ::: "memory");
;             xb_add(&bar[XB_XGEN(b.x)], 1u);
;             asm volatile("s_waitcnt vmcnt(0)" ::: "memory");
;         } else {
;             XB_SPIN(xb_ld(&bar[XB_XGEN(b.x)]) == gen, bar);
;             asm volatile("" ::: "memory");
;             asm volatile("s_waitcnt vmcnt(0)" ::: "memory");
;         }
;     }
;     __syncthreads();
; }
; __global__ void __launch_bounds__(512, 2) fwd_mega(Args a) {
;     ...
;         xcd_barrier(bar);
;         {
;             pg8::Gemm g{WSP(WS_MG), WSP(WS_WO2), M, D, D, 1 << 20, 0}; pg8::StaticOrder S; S.init(M, D, G, bx);
.LBB0_709:
	s_or_b64 exec, exec, s[12:13]
.LBB0_710:
	s_or_b64 exec, exec, s[6:7]
	v_mov_b32_e32 v166, v0
	s_waitcnt lgkmcnt(0)
	s_barrier
	s_and_b64 vcc, exec, s[74:75]
	v_readfirstlane_b32 s4, v166
	s_cbranch_vccnz .LBB0_773
	s_ashr_i32 s24, s2, 31
	s_mov_b64 s[12:13], s[26:27]
	s_lshr_b32 s5, s24, 29
	s_add_i32 s8, s2, s5
	s_and_b32 s5, s8, -8
	s_sub_i32 s9, s2, s5
	s_cmp_gt_i32 s9, -1
	s_cbranch_scc0 .LBB0_713
	s_lshl_b32 s5, s9, 5
	s_cbranch_execz .LBB0_714
	s_branch .LBB0_715

; template <class Epi, class Sched, bool ALIGN_EPI = false, bool SP2 = false, bool PAIR_ACC = false>
; __device__ __forceinline__ void gemm_phase(PG8_LAS unsigned char* lds, const Gemm g, const Sched& S, const Epi& E) {
;     int tid_ = threadIdx.x; asm volatile("" : "+v"(tid_));
;     const int tid = tid_, wid = __builtin_amdgcn_readfirstlane(tid >> 6), lane = tid & 63, wr = wid >> 2, wc = wid & 3, fr = lane & 15, fq = lane >> 4;
;     const int K = g.K, nt = K / BK;
;     unsigned voffA[2], voffB[2];
; #pragma unroll
;     for (int i = 0; i < 2; ++i) { int R, C; stage_rc(tid * 16 + i * 8192, R, C); const int Rb = Epi::PERM ? ((R & ~31) + perm32(R & 31)) : R;
;         voffA[i] = (unsigned)(R * K + C) * 2u; voffB[i] = (unsigned)(Rb * K + C) * 2u; }
;     const size_t kstep = (size_t)(BK * 2);
;     const size_t hstep = (size_t)HALF * K * 2;
;     const size_t tstep = 2 * hstep;
;     const unsigned ldsw = (unsigned)wid * 1024u;
;     const int aoff = lds_byte(wr * 64 + fr, fq * 8), boff = lds_byte(wc * 32 + fr, fq * 8);
;     ...
;     Unit cur, nxt; int ui = 0;
;     if (!S.next(0, cur)) return;
;     f32x4 acc[2][2][4][2];
; #pragma unroll
;     for (int a = 0; a < 2; ++a)
; #pragma unroll
;         for (int b = 0; b < 2; ++b)
; #pragma unroll
;             for (int m = 0; m < 4; ++m)
; #pragma unroll
;                 for (int n = 0; n < 2; ++n) acc[a][b][m][n] = (f32x4){0.f, 0.f, 0.f, 0.f};
;     bf16x8 At[4][2], B0[2][2], B1[2][2];
;     const char* cA = (const char*)g.A + (size_t)cur.pm * tstep + (size_t)(cur.pn / g.a_div) * g.a_sel; const char* cB = (const char*)g.Bt + (size_t)cur.pn * tstep;
;     S.a_ready(cur);
;     if constexpr (SP2) {
;         PG8_STAGE(PG8_SB(0, 0), cB, voffB); PG8_STAGE(PG8_SB(0, 1), cB + hstep, voffB); PG8_STAGE(PG8_SA(0, 0), cA, voffA); PG8_STAGE(PG8_SA(0, 1), cA + hstep, voffA);
;         if (wr == 1) PG8_BAR;
;         PG8_WAIT_V(2); PG8_BAR;
;         PG8_STAGE(PG8_SB(1, 0), cB + kstep, voffB); PG8_STAGE(PG8_SA(1, 0), cA + kstep, voffA); PG8_STAGE(PG8_SB(1, 1), cB + hstep + kstep, voffB);
;         PG8_WAIT_V(6); PG8_BAR;
; __device__ __forceinline__ void xcd_barrier(const XcdBarrier& b) {
;     ...
;             asm volatile("" ::: "memory");
;             xb_add(&bar[XB_XGEN(b.x)], 1u);
;             asm volatile("s_waitcnt vmcnt(0)" ::: "memory");
;         } else {
;             XB_SPIN(xb_ld(&bar[XB_XGEN(b.x)]) == gen, bar);
.LBB0_824:
	s_or_b64 exec, exec, s[12:13]
.LBB0_825:
	s_or_b64 exec, exec, s[6:7]
	s_cmpk_lt_i32 s2, 0x580
	s_cselect_b64 s[4:5], -1, 0
	v_writelane_b32 v246, s4, 16
	v_mov_b32_e32 v13, v0
	s_waitcnt lgkmcnt(0)
	v_writelane_b32 v246, s5, 17
	s_barrier
	s_cmpk_gt_i32 s2, 0x57f
	v_readfirstlane_b32 s9, v13
	v_writelane_b32 v246, s74, 14
	s_nop 1
	v_writelane_b32 v246, s75, 15
	s_cbranch_scc1 .LBB0_850
	v_lshlrev_b32_e32 v2, 4, v13
	v_add_u32_e32 v3, 0x2000, v2
	v_ashrrev_i32_e32 v4, 31, v3
	v_lshrrev_b32_e32 v4, 22, v4
	v_add_u32_e32 v4, v3, v4
	v_ashrrev_i32_e32 v10, 10, v4
	v_mul_i32_i24_e32 v4, 0x400, v10
	v_sub_u32_e32 v3, v3, v4
	v_lshrrev_b32_e32 v4, 4, v3
	v_bitop3_b32 v3, v4, v3, 32 bitop3:0x6c
	v_ashrrev_i32_e32 v4, 31, v3
	v_lshrrev_b32_e32 v4, 26, v4
	v_add_u32_e32 v4, v3, v4
	v_lshlrev_b32_e32 v5, 3, v10
	v_ashrrev_i32_e32 v11, 6, v4
	v_and_b32_e32 v5, -16, v5
	v_add_u32_e32 v5, v11, v5
	v_and_b32_e32 v6, 3, v11
	s_mov_b32 s8, 0x1fffe0
	v_lshrrev_b32_e32 v7, 2, v5
	v_lshlrev_b32_e32 v8, 1, v5
	v_and_b32_e32 v4, 0xc0, v4
	v_and_or_b32 v6, v5, s8, v6
	v_and_b32_e32 v7, 4, v7
	v_and_b32_e32 v8, 24, v8
	v_sub_u32_e32 v3, v3, v4
	v_mov_b32_e32 v4, 1
	v_or3_b32 v6, v6, v7, v8
	v_lshlrev_b32_e32 v7, 5, v10
	v_ashrrev_i16_sdwa v3, v4, sext(v3) dst_sel:DWORD dst_unused:UNUSED_PAD src0_sel:DWORD src1_sel:BYTE_0
	v_and_b32_e32 v7, 32, v7
	v_bfe_i32 v12, v3, 0, 16
	v_add_lshl_u32 v3, v7, v12, 1
	v_lshl_add_u32 v174, v6, 11, v3
	v_lshl_add_u32 v176, v5, 11, v3
	v_bfe_i32 v3, v13, 27, 1
	v_lshrrev_b32_e32 v3, 22, v3
	v_add_u32_e32 v3, v2, v3
	s_mov_b64 s[6:7], s[26:27]
	v_and_b32_e32 v3, 0xfffffc00, v3
	v_sub_u32_e32 v2, v2, v3
	v_lshrrev_b32_e32 v3, 4, v2
	v_ashrrev_i32_e32 v5, 31, v13
	v_bitop3_b32 v2, v3, v2, 32 bitop3:0x6c
	v_lshrrev_b32_e32 v5, 26, v5
	v_ashrrev_i32_e32 v3, 31, v2
	v_add_u32_e32 v5, v13, v5
	s_waitcnt lgkmcnt(0)
	s_add_u32 s4, s6, 0x4b00000
	v_lshrrev_b32_e32 v3, 26, v3
	v_ashrrev_i32_e32 v15, 6, v5
	s_addc_u32 s5, s7, 0
	v_add_u32_e32 v3, v2, v3
	v_lshlrev_b32_e32 v5, 3, v15
	s_add_u32 s23, s6, 0x1a80000
	v_ashrrev_i32_e32 v14, 6, v3
	v_and_b32_e32 v5, -16, v5
	s_addc_u32 s24, s7, 0
	v_add_u32_e32 v5, v14, v5
	v_and_b32_e32 v6, 3, v14
	s_ashr_i32 s34, s2, 31
	v_and_or_b32 v6, v5, s8, v6
	s_lshr_b32 s8, s34, 29
	s_add_i32 s8, s2, s8
	s_ashr_i32 s41, s9, 6
	s_ashr_i32 s10, s8, 3
	s_and_b32 s8, s8, -8
	s_ashr_i32 s40, s9, 8
	s_lshl_b32 s25, s41, 10
	s_sub_i32 s8, s2, s8
	s_cmp_lt_i32 s8, 0
	s_movk_i32 s35, 0xb1
	s_cselect_b32 s11, s35, 0xb0
	s_mul_i32 s8, s11, s8
	s_add_i32 s8, s8, s10
	s_mul_hi_i32 s10, s8, 0x2e8ba2e9
	s_lshr_b32 s11, s10, 31
	s_ashr_i32 s10, s10, 5
	s_add_i32 s10, s10, s11
	s_lshl_b32 s11, s10, 3
	s_mulk_i32 s10, 0xb0
	s_sub_i32 s10, s8, s10
	s_sext_i32_i16 s8, s10
	s_bfe_u32 s8, s8, 0x3001c
	s_add_i32 s12, s10, s8
	s_sext_i32_i16 s8, s12
	s_and_b32 s12, s12, 0xfff8
	s_sub_i32 s10, s10, s12
	s_sext_i32_i16 s10, s10
	v_lshrrev_b32_e32 v7, 2, v5
	v_lshlrev_b32_e32 v8, 1, v5
	v_and_b32_e32 v3, 0xc0, v3
	s_lshr_b32 s8, s8, 3
	s_add_i32 s70, s11, s10
	v_and_b32_e32 v7, 4, v7
	v_and_b32_e32 v8, 24, v8
	v_sub_u32_e32 v2, v2, v3
	s_ashr_i32 s71, s70, 31
	s_bfe_i64 s[12:13], s[8:9], 0x100000
	v_or3_b32 v6, v6, v7, v8
	v_lshlrev_b32_e32 v7, 5, v15
	v_ashrrev_i16_sdwa v2, v4, sext(v2) dst_sel:DWORD dst_unused:UNUSED_PAD src0_sel:DWORD src1_sel:BYTE_0
	s_lshl_b64 s[10:11], s[70:71], 19
	s_lshl_b64 s[12:13], s[12:13], 19
	v_and_b32_e32 v7, 32, v7
	v_bfe_i32 v16, v2, 0, 16
	s_add_u32 s38, s23, s12
	v_add_lshl_u32 v2, v7, v16, 1
	s_addc_u32 s39, s24, s13
	s_add_i32 s36, s25, 0
	v_lshl_add_u32 v178, v6, 11, v2
	s_add_i32 m0, s36, 0x10000
	v_lshl_add_u32 v180, v5, 11, v2
	global_load_lds_dwordx4 v178, s[38:39]
	s_add_i32 m0, s36, 0x12000
	s_add_u32 s12, s38, 0x40000
	global_load_lds_dwordx4 v174, s[38:39]
	s_addc_u32 s13, s39, 0
	s_add_i32 m0, s36, 0x14000
	v_mov_b32_e32 v179, 0
	global_load_lds_dwordx4 v178, s[12:13]
	s_add_i32 m0, s36, 0x16000
	s_add_u32 s10, s4, s10
	s_addc_u32 s11, s5, s11
	s_add_i32 s37, s36, 0x2000
	global_load_lds_dwordx4 v174, s[12:13]
	s_mov_b32 m0, s36
	s_add_u32 s12, s10, 0x40000
	global_load_lds_dwordx4 v180, s[10:11]
	s_mov_b32 m0, s37
	s_addc_u32 s13, s11, 0
	s_add_i32 s42, s36, 0x4000
	global_load_lds_dwordx4 v176, s[10:11]
	s_mov_b32 m0, s42
	s_add_i32 s43, s36, 0x6000
	global_load_lds_dwordx4 v180, s[12:13]
	s_mov_b32 m0, s43
	v_mov_b32_e32 v175, v179
	global_load_lds_dwordx4 v176, s[12:13]
	v_readlane_b32 s12, v247, 36
	v_readlane_b32 s13, v247, 37
	v_readlane_b32 s14, v247, 38
	v_readlane_b32 s15, v247, 39
	s_nop 4
	v_mov_b32_e32 v181, v179
	v_mov_b32_e32 v177, v179
	s_cmp_eq_u32 s40, 1
	s_mov_b32 s44, 0
	v_lshl_add_u64 v[8:9], s[38:39], 0, v[178:179]
	v_lshl_add_u64 v[6:7], s[38:39], 0, v[174:175]
	v_lshl_add_u64 v[2:3], s[10:11], 0, v[180:181]
	s_cselect_b64 s[16:17], -1, 0
	s_cmp_lg_u32 s40, 1
	v_lshl_add_u64 v[4:5], s[10:11], 0, v[176:177]
	s_cbranch_scc1 .LBB0_828
	s_barrier

;     __host__ __device__ void init(int M, int N, int G_, int c_) { base.init(M, N, G_, c_); G = G_; c = c_; }
;     __host__ __device__ void init(int M, int G_, int c_) { base.init(M, 1024, G_, c_); }
;     __host__ __device__ bool next(int i, Unit& u) const { Unit b; if (!base.next(i >> 1, b)) return false; u.pm = b.pm; u.pn = b.pn + 4 * (i & 1); return true; }
; __device__ __forceinline__ unsigned xb_ld(unsigned* p)              { return __hip_atomic_load(p, __ATOMIC_RELAXED, __HIP_MEMORY_SCOPE_AGENT); }
; __device__ __forceinline__ unsigned xb_add(unsigned* p, unsigned v) { return __hip_atomic_fetch_add(p, v, __ATOMIC_RELAXED, __HIP_MEMORY_SCOPE_AGENT); }
; #define XB_SPIN(cond, bar) do { unsigned _sp = 0; while (cond) { __builtin_amdgcn_s_sleep(1); \
;     if ((++_sp & 255u) == 0u) { if (xb_ld(&(bar)[XB_TMO])) break; if (_sp > XB_SPIN_CAP) { atomicAdd(&(bar)[XB_TMO], 1u); break; } } } } while (0)
; __device__ __forceinline__ void xcd_barrier(const XcdBarrier& b) {
;     ...
;             asm volatile("" ::: "memory");
;             xb_add(&bar[XB_XGEN(b.x)], 1u);
;             asm volatile("s_waitcnt vmcnt(0)" ::: "memory");
;         } else {
;             XB_SPIN(xb_ld(&bar[XB_XGEN(b.x)]) == gen, bar);
;             asm volatile("" ::: "memory");
;             asm volatile("s_waitcnt vmcnt(0)" ::: "memory");
;         }
;     }
;     __syncthreads();
; __global__ void __launch_bounds__(512, 2) fwd_mega(Args a) {
;     ...
;             pg8::Gemm g{WSP(WS_ACT), WSP(l == 0 ? WS_WD : WS_WD1), M, D, FF, 1 << 20, 0}; pg8::StaticOrder S; S.init(M, D, G, bx);
;             {
;                 const float* cw = INF(18) + (size_t)l * 3 * FF; const float* cbp = INF(19) + (size_t)l * FF;
;                 const float* RA = (const float*)(a.ws + WS_RAWA); const float* RU = (const float*)(a.ws + WS_RAWU); const float* TA = (const float*)(a.ws + WS_TAILA);
;                 pg8::Unit fu;
;                 for (int i = 0; S.next(i, fu); ++i) {
;                     if ((fu.pm & 15) == 0) continue;
;                     for (int idx = threadIdx.x; idx < 2 * FF; idx += 512) {
;                         const int j = idx / FF, f = idx % FF; const size_t cur = (size_t)fu.pm * 2 * FF, prv = (size_t)(fu.pm - 1) * 2 * FF;
;                         const float a2 = RA[cur + j * FF + f], a1 = (j == 0) ? TA[prv + FF + f] : RA[cur + f], a0 = (j == 0) ? TA[prv + f] : TA[prv + FF + f];
.LBB0_901:
	s_or_b64 exec, exec, s[12:13]
.LBB0_902:
	s_or_b64 exec, exec, s[6:7]
	s_waitcnt lgkmcnt(0)
	s_barrier
	s_mov_b64 s[12:13], s[26:27]
	v_readlane_b32 s8, v247, 36
	v_readlane_b32 s9, v247, 37
	v_readlane_b32 s10, v247, 38
	v_readlane_b32 s11, v247, 39
	s_nop 4
	s_mov_b32 s23, 0
	v_mov_b64_e32 v[2:3], 0x100
	v_mov_b64_e32 v[4:5], 0xff
	s_waitcnt lgkmcnt(0)
	s_add_u32 s20, s12, 0x6b00000
	s_addc_u32 s21, s13, 0
	s_add_u32 s14, s12, 0x200000
	s_addc_u32 s15, s13, 0
	s_add_u32 s16, s12, 0x380000
	s_addc_u32 s17, s13, 0
	s_add_u32 s4, s12, 0x500000
	s_addc_u32 s5, s13, 0
	s_ashr_i32 s67, s3, 31
	s_ashr_i32 s65, s2, 31
	s_movk_i32 s24, 0x1600
	s_movk_i32 s25, 0xaff
	v_mov_b32_e32 v7, 0
	s_movk_i32 s30, 0x2000
	s_movk_i32 s31, 0x5000
	s_movk_i32 s34, 0x7fff
	s_movk_i32 s35, 0x13ff
	v_mov_b32_e32 v10, 0xb00
	v_mov_b64_e32 v[8:9], s[20:21]
	s_branch .LBB0_905

;     __host__ __device__ bool next(int i, Unit& u) const { Unit b; if (!base.next(i >> 1, b)) return false; u.pm = b.pm; u.pn = b.pn + 4 * (i & 1); return true; }
; __device__ __forceinline__ unsigned xb_ld(unsigned* p)              { return __hip_atomic_load(p, __ATOMIC_RELAXED, __HIP_MEMORY_SCOPE_AGENT); }
; __device__ __forceinline__ unsigned xb_add(unsigned* p, unsigned v) { return __hip_atomic_fetch_add(p, v, __ATOMIC_RELAXED, __HIP_MEMORY_SCOPE_AGENT); }
; #define XB_SPIN(cond, bar) do { unsigned _sp = 0; while (cond) { __builtin_amdgcn_s_sleep(1); \
;     if ((++_sp & 255u) == 0u) { if (xb_ld(&(bar)[XB_TMO])) break; if (_sp > XB_SPIN_CAP) { atomicAdd(&(bar)[XB_TMO], 1u); break; } } } } while (0)
;     __host__ __device__ bool next(int i, Unit& u) const {
;         const long L = (long)i * G + c; if (L >= nwg) return false;
;         int wgid = (int)L; { const int q = nwg / NXCD, r = nwg % NXCD, xcd = wgid % NXCD, off = wgid / NXCD; wgid = (xcd < r ? xcd * (q + 1) : r * (q + 1) + (xcd - r) * q) + off; }
;         const int nig = WGM * nN, gid = wgid / nig, fm = gid * WGM, gsz = (nM - fm) < WGM ? (nM - fm) : WGM;
;         u.pm = fm + ((wgid % nig) % gsz); u.pn = (wgid % nig) / gsz; return true;
; __device__ __forceinline__ void xcd_barrier(const XcdBarrier& b) {
;     ...
;             asm volatile("" ::: "memory");
;             xb_add(&bar[XB_XGEN(b.x)], 1u);
;             asm volatile("s_waitcnt vmcnt(0)" ::: "memory");
;         } else {
;             XB_SPIN(xb_ld(&bar[XB_XGEN(b.x)]) == gen, bar);
;             asm volatile("" ::: "memory");
;             asm volatile("s_waitcnt vmcnt(0)" ::: "memory");
;         }
;     }
;     __syncthreads();
.LBB0_1064:
	s_or_b64 exec, exec, s[12:13]
.LBB0_1065:
	s_or_b64 exec, exec, s[6:7]
	v_readlane_b32 s4, v246, 8
	v_readlane_b32 s5, v246, 9
	v_mov_b32_e32 v10, v0
	s_waitcnt lgkmcnt(0)
	v_cndmask_b32_e64 v2, 0, 1, s[4:5]
	s_barrier
	v_cmp_ne_u32_e64 s[6:7], 1, v2
	s_andn2_b64 vcc, exec, s[4:5]
	v_readfirstlane_b32 s4, v10
	s_cbranch_vccnz .LBB0_1068
	s_mov_b64 s[8:9], 0
	s_cmpk_gt_i32 s2, 0x53f
	s_mov_b64 s[10:11], 0
	s_cbranch_scc1 .LBB0_1069
	s_lshr_b32 s5, s65, 29
	s_add_i32 s5, s2, s5
	s_ashr_i32 s10, s5, 3
	s_and_b32 s5, s5, -8
	s_sub_i32 s5, s2, s5
	s_cmp_lt_i32 s5, 0
	s_movk_i32 s11, 0xa9
	s_cselect_b32 s11, s11, 0xa8
	s_mul_i32 s5, s11, s5
	s_add_i32 s5, s5, s10
	s_mul_hi_i32 s10, s5, 0x30c30c31
	s_lshr_b32 s11, s10, 31
	s_ashr_i32 s10, s10, 5
	s_add_i32 s10, s10, s11
	s_lshl_b32 s11, s10, 3
	s_mulk_i32 s10, 0xa8
	s_sub_i32 s5, s5, s10
	s_sext_i32_i16 s10, s5
	s_bfe_u32 s10, s10, 0x3001c
	s_add_i32 s10, s5, s10
	s_sext_i32_i16 s12, s10
	s_and_b32 s10, s10, 0xfff8
	s_sub_i32 s5, s5, s10
	s_sext_i32_i16 s5, s5
	s_add_i32 s14, s11, s5
	s_ashr_i32 s18, s12, 3
	s_mov_b64 s[10:11], -1
	s_branch .LBB0_1069

; __device__ __forceinline__ void attn_unit(LAS unsigned char* lds, bf16* Q, const bf16* Kg, const bf16* Vg, const float* snk, int unit, int tid) {
;     const int lane = tid & 63, wave = tid >> 6, fr = lane & 15, fq = lane >> 4;
;     const int b = unit >> 6, n = (unit >> 1) & 31, h = unit & 1, r0 = b * SEQ + n * 128, hq = 8 * h + wave;
;     const v4u zero4 = {0u, 0u, 0u, 0u};
;     bf16* qbase = Q + (size_t)(r0 + fr) * 1024 + hq * 64;
;     bf16x8_t qf[8][2];
; #pragma unroll
;     for (int mt = 0; mt < 8; ++mt) { qf[mt][0] = *(const bf16x8_t*)(qbase + (size_t)mt * 16 * 1024 + 8 * fq); qf[mt][1] = *(const bf16x8_t*)(qbase + (size_t)mt * 16 * 1024 + 32 + 8 * fq); }
; #pragma unroll
;     for (int i = 0; i < 4; ++i) { const int idx = tid + 512 * i, j = idx >> 3, c = idx & 7, p = n * 128 - 128 + j;
;         v4u w = zero4; if (p >= 0) w = *(const v4u*)(Kg + (size_t)(b * SEQ + p) * 128 + h * 64 + c * 8);
;         *(LAS v4u*)(lds + j * ATT_KP + c * 16) = w; }
; #pragma unroll
;     for (int i = 0; i < 2; ++i) { const int idx = tid + 512 * i, j = (idx >> 3) * 2, c = idx & 7, p = n * 128 - 128 + j;
;         v4u w0 = zero4, w1 = zero4;
;         if (p >= 0) { w0 = *(const v4u*)(Vg + (size_t)(b * SEQ + p) * 128 + h * 64 + c * 8); w1 = *(const v4u*)(Vg + (size_t)(b * SEQ + p + 1) * 128 + h * 64 + c * 8); }
;         const unsigned A0[4] = {w0.x, w0.y, w0.z, w0.w}, A1[4] = {w1.x, w1.y, w1.z, w1.w};
; #pragma unroll
;         for (int e = 0; e < 8; ++e) { const unsigned lo = (e & 1) ? (A0[e >> 1] >> 16) : (A0[e >> 1] & 0xffffu), hi = (e & 1) ? (A1[e >> 1] & 0xffff0000u) : (A1[e >> 1] << 16);
;             *(LAS unsigned*)(lds + ATT_VOFF + (8 * c + e) * ATT_VP + j * 2) = lo | hi; } }
;     __syncthreads();
;     const float sink = snk[hq] * 1.4426950408889634f;
;     bool lo_ok[4];
; #pragma unroll
;     for (int i = 0; i < 4; ++i) lo_ok[i] = (4 * fq + i - fr) > 0;
; #pragma unroll
;     for (int mt = 0; mt < 8; ++mt) {
;         f32x4 st[9];
; #pragma unroll
;         for (int kb = 0; kb < 9; ++kb) { const LAS unsigned char* kp = lds + (16 * (mt + kb) + fr) * ATT_KP + 16 * fq;
; __device__ __forceinline__ void sgu_unit(LAS unsigned char* lds, bf16* U, const bf16* VS, const float* SGS, const float* lnw, const float* lnb, const v4u* WF, const float* bsl, int unit, int tid) {
;     const int lane = tid & 63, wave = tid >> 6, fr = lane & 15, fq = lane >> 4;
.LBB0_1393:
	s_or_b64 exec, exec, s[12:13]
.LBB0_1394:
	s_or_b64 exec, exec, s[6:7]
	v_readlane_b32 s4, v246, 18
	v_readlane_b32 s5, v246, 19
	v_mov_b32_e32 v161, v0
	s_andn2_b64 vcc, exec, s[4:5]
	s_waitcnt lgkmcnt(0)
	s_barrier
	s_cbranch_vccnz .LBB0_1415
	s_movk_i32 s4, 0x80
	v_cmp_gt_i32_e64 s[6:7], s4, v161
	v_ashrrev_i32_e32 v169, 6, v161
	s_movk_i32 s4, 0x4400
	v_mul_lo_u32 v5, v169, s4
	s_mov_b64 s[4:5], s[26:27]
	v_readlane_b32 s28, v247, 14
	v_readlane_b32 s29, v247, 15
	v_readlane_b32 s30, v247, 16
	v_readlane_b32 s31, v247, 17
	v_readlane_b32 s16, v247, 18
	v_readlane_b32 s17, v247, 19
	v_readlane_b32 s18, v247, 22
	v_readlane_b32 s19, v247, 23
	s_nop 4
	v_and_b32_e32 v6, 7, v161
	v_add_u32_e32 v8, 0x200, v161
	v_lshlrev_b32_e32 v170, 3, v6
	s_waitcnt lgkmcnt(0)
	s_add_u32 s38, s4, 0x4b00000
	s_addc_u32 s39, s5, 0
	s_add_u32 s30, s30, 0x1000
	s_addc_u32 s31, s31, 0
	s_add_u32 s40, s16, 0x1000
	v_mul_u32_u24_e32 v10, 0x110, v6
	v_bfe_u32 v15, v161, 4, 2
	v_lshlrev_b32_e32 v4, 4, v6
	s_waitcnt vmcnt(1)
	v_mul_u32_u24_e32 v20, 0x1080, v6
	v_ashrrev_i32_e32 v6, 2, v8
	s_addc_u32 s41, s17, 0
	v_add_u32_e32 v9, 0x400, v161
	v_and_b32_e32 v176, -2, v6
	v_lshlrev_b32_e32 v6, 2, v15
	s_add_u32 s44, s18, 0x1000
	v_and_b32_e32 v3, 63, v161
	v_and_b32_e32 v163, 15, v161
	v_ashrrev_i32_e32 v172, 3, v8
	v_ashrrev_i32_e32 v173, 3, v9
	v_add_u32_e32 v9, 0x600, v161
	v_or_b32_e32 v8, 2, v6
	s_addc_u32 s45, s19, 0
	v_mov_b32_e32 v147, 0
	v_ashrrev_i32_e32 v174, 3, v9
	v_ashrrev_i32_e32 v9, 2, v161
	v_cmp_gt_u32_e64 s[12:13], v8, v163
	v_or_b32_e32 v8, 3, v6
	v_lshlrev_b32_e32 v146, 4, v3
	s_add_u32 s46, s4, 0xf400000
	v_add_u32_e32 v3, 0, v5
	v_lshrrev_b32_e32 v5, 1, v161
	v_bfe_u32 v2, v161, 3, 3
	v_and_b32_e32 v175, -2, v9
	v_cmp_gt_u32_e64 s[14:15], v8, v163
	v_lshl_add_u64 v[8:9], s[4:5], 0, v[146:147]
	s_mov_b64 s[16:17], 0x680000
	s_addc_u32 s47, s5, 0
	v_and_b32_e32 v146, 24, v5
	v_lshlrev_b32_e32 v167, 3, v161
	v_lshlrev_b32_e32 v7, 11, v2
	v_lshlrev_b32_e32 v11, 2, v2
	v_lshlrev_b32_e32 v12, 4, v2
	v_bfe_u32 v2, v161, 3, 1
	v_lshl_add_u64 v[148:149], v[8:9], 0, s[16:17]
	v_lshl_add_u64 v[8:9], s[4:5], 0, v[146:147]
	s_mov_b64 s[16:17], 0x9300000
	s_add_u32 s50, s4, 0x6b00000
	v_mov_b32_e32 v5, v147
	v_and_or_b32 v2, v167, 56, v2
	v_lshl_add_u64 v[150:151], v[8:9], 0, s[16:17]
	s_addc_u32 s51, s5, 0
	v_add_u32_e32 v8, 0, v4
	v_lshl_add_u64 v[4:5], s[4:5], 0, v[4:5]
	s_mov_b64 s[4:5], 0x8b00000
	v_mul_u32_u24_e32 v14, 0x110, v2
	v_lshlrev_b32_e32 v2, 3, v15
	v_lshl_add_u64 v[152:153], v[4:5], 0, s[4:5]
	s_mov_b64 s[4:5], 0x8f00000
	v_lshl_add_u32 v9, v15, 4, 0
	v_and_b32_e32 v13, 48, v161
	v_ashrrev_i32_e32 v171, 3, v161
	s_movk_i32 s20, 0x90
	v_add3_u32 v177, v3, v10, v11
	v_lshl_add_u64 v[154:155], v[4:5], 0, s[4:5]
	v_sub_u32_e32 v10, v9, v2
	s_movk_i32 s4, 0x210
	v_mul_lo_u32 v16, v171, s20
	v_mul_lo_u32 v17, v172, s20
	v_mul_lo_u32 v18, v173, s20
	v_mul_lo_u32 v19, v174, s20
	v_add_u32_e32 v3, v3, v13
	v_lshl_add_u32 v4, v175, 1, 0
	v_lshl_add_u32 v5, v176, 1, 0
	v_mad_u32_u24 v179, v163, s4, v10
	s_lshl_b32 s4, s2, 2
	v_ashrrev_i32_e32 v165, 7, v161
	v_and_b32_e32 v168, 64, v161
	v_cmp_gt_u32_e64 s[8:9], v6, v163
	v_cmp_lt_u32_e64 s[10:11], v6, v163
	s_mov_b32 s49, 0
	v_mad_u32_u24 v178, v163, s20, v9
	s_addk_i32 s4, 0xfc00
	s_lshl_b32 s5, s3, 2
	s_lshl_b32 s24, s2, 6
	s_lshl_b32 s25, s3, 6
	s_movk_i32 s34, 0x1000
	s_movk_i32 s35, 0x2000
	s_movk_i32 s36, 0x3000
	s_movk_i32 s37, 0x4000
	s_mov_b32 s52, 0x3a800000
	s_mov_b32 s42, 0x800000
	v_lshlrev_b32_e32 v180, 1, v7
	s_mov_b32 s43, 0x8000
	s_mov_b32 s53, 0x10000
	s_mov_b32 s54, 0x18000
	s_mov_b32 s55, 0x20000
	s_mov_b32 s56, 0x28000
	s_mov_b32 s57, 0x30000
	s_mov_b32 s58, 0x38000
	v_add_u32_e32 v181, 0, v12
	s_mov_b32 s59, 0xffff0000
	v_add_u32_e32 v182, v3, v14
	v_lshlrev_b32_e32 v146, 1, v2
	v_add_u32_e32 v183, v8, v16
	v_add_u32_e32 v184, v8, v17
	v_add_u32_e32 v185, v8, v18
	v_add_u32_e32 v186, v8, v19
	s_mov_b32 s60, 0xffff
	v_add_u32_e32 v187, v4, v20
	v_add_u32_e32 v188, v5, v20
	s_mov_b32 s61, 0x3fb8aa3b
	v_lshlrev_b32_e32 v156, 1, v6
	v_mbcnt_hi_u32_b32 v189, -1, v1
	v_mov_b32_e32 v190, 0xff800000
	s_mov_b32 s62, s2
	s_branch .LBB0_1398

;     __host__ __device__ bool next(int i, Unit& u) const { Unit b; if (!base.next(i >> 1, b)) return false; u.pm = b.pm; u.pn = b.pn + 4 * (i & 1); return true; }
; __device__ __forceinline__ unsigned xb_ld(unsigned* p)              { return __hip_atomic_load(p, __ATOMIC_RELAXED, __HIP_MEMORY_SCOPE_AGENT); }
; __device__ __forceinline__ unsigned xb_add(unsigned* p, unsigned v) { return __hip_atomic_fetch_add(p, v, __ATOMIC_RELAXED, __HIP_MEMORY_SCOPE_AGENT); }
; #define XB_SPIN(cond, bar) do { unsigned _sp = 0; while (cond) { __builtin_amdgcn_s_sleep(1); \
;     if ((++_sp & 255u) == 0u) { if (xb_ld(&(bar)[XB_TMO])) break; if (_sp > XB_SPIN_CAP) { atomicAdd(&(bar)[XB_TMO], 1u); break; } } } } while (0)
;     __host__ __device__ bool next(int i, Unit& u) const {
;         const long L = (long)i * G + c; if (L >= nwg) return false;
;         int wgid = (int)L; { const int q = nwg / NXCD, r = nwg % NXCD, xcd = wgid % NXCD, off = wgid / NXCD; wgid = (xcd < r ? xcd * (q + 1) : r * (q + 1) + (xcd - r) * q) + off; }
;         const int nig = WGM * nN, gid = wgid / nig, fm = gid * WGM, gsz = (nM - fm) < WGM ? (nM - fm) : WGM;
;         u.pm = fm + ((wgid % nig) % gsz); u.pn = (wgid % nig) / gsz; return true;
; __device__ __forceinline__ void xcd_barrier(const XcdBarrier& b) {
;     ...
;             asm volatile("" ::: "memory");
;             xb_add(&bar[XB_XGEN(b.x)], 1u);
;             asm volatile("s_waitcnt vmcnt(0)" ::: "memory");
;         } else {
;             XB_SPIN(xb_ld(&bar[XB_XGEN(b.x)]) == gen, bar);
;             asm volatile("" ::: "memory");
;             asm volatile("s_waitcnt vmcnt(0)" ::: "memory");
;         }
;     }
;     __syncthreads();
.LBB0_1466:
	s_or_b64 exec, exec, s[12:13]
.LBB0_1467:
	s_or_b64 exec, exec, s[6:7]
	s_waitcnt lgkmcnt(0)
	s_barrier
	s_mov_b64 s[6:7], s[26:27]
	v_mov_b32_e32 v10, v0
	s_and_b64 vcc, exec, s[74:75]
	v_readfirstlane_b32 s20, v10
	s_cbranch_vccnz .LBB0_1473
	s_lshr_b32 s4, s65, 29
	s_add_i32 s4, s2, s4
	s_and_b32 s5, s4, -8
	s_sub_i32 s5, s2, s5
	s_cmp_gt_i32 s5, -1
	s_cbranch_scc0 .LBB0_1470
	s_lshl_b32 s10, s5, 5
	s_cbranch_execz .LBB0_1471
	s_branch .LBB0_1472

;     __host__ __device__ bool next(int i, Unit& u) const { Unit b; if (!base.next(i >> 1, b)) return false; u.pm = b.pm; u.pn = b.pn + 4 * (i & 1); return true; }
; __device__ __forceinline__ unsigned xb_ld(unsigned* p)              { return __hip_atomic_load(p, __ATOMIC_RELAXED, __HIP_MEMORY_SCOPE_AGENT); }
; __device__ __forceinline__ unsigned xb_add(unsigned* p, unsigned v) { return __hip_atomic_fetch_add(p, v, __ATOMIC_RELAXED, __HIP_MEMORY_SCOPE_AGENT); }
; #define XB_SPIN(cond, bar) do { unsigned _sp = 0; while (cond) { __builtin_amdgcn_s_sleep(1); \
;     if ((++_sp & 255u) == 0u) { if (xb_ld(&(bar)[XB_TMO])) break; if (_sp > XB_SPIN_CAP) { atomicAdd(&(bar)[XB_TMO], 1u); break; } } } } while (0)
;     __host__ __device__ bool next(int i, Unit& u) const {
;         const long L = (long)i * G + c; if (L >= nwg) return false;
;         int wgid = (int)L; { const int q = nwg / NXCD, r = nwg % NXCD, xcd = wgid % NXCD, off = wgid / NXCD; wgid = (xcd < r ? xcd * (q + 1) : r * (q + 1) + (xcd - r) * q) + off; }
;         const int nig = WGM * nN, gid = wgid / nig, fm = gid * WGM, gsz = (nM - fm) < WGM ? (nM - fm) : WGM;
;         u.pm = fm + ((wgid % nig) % gsz); u.pn = (wgid % nig) / gsz; return true;
; __device__ __forceinline__ void xcd_barrier(const XcdBarrier& b) {
;     ...
;             asm volatile("" ::: "memory");
;             xb_add(&bar[XB_XGEN(b.x)], 1u);
;             asm volatile("s_waitcnt vmcnt(0)" ::: "memory");
;         } else {
;             XB_SPIN(xb_ld(&bar[XB_XGEN(b.x)]) == gen, bar);
;             asm volatile("" ::: "memory");
;             asm volatile("s_waitcnt vmcnt(0)" ::: "memory");
;         }
;     }
;     __syncthreads();
.LBB0_1612:
	s_or_b64 exec, exec, s[12:13]
.LBB0_1613:
	s_or_b64 exec, exec, s[6:7]
	v_mov_b32_e32 v168, v0
	s_waitcnt lgkmcnt(0)
	s_barrier
	s_and_b64 vcc, exec, s[74:75]
	v_readfirstlane_b32 s4, v168
	s_cbranch_vccnz .LBB0_1676
	s_lshr_b32 s5, s65, 29
	s_add_i32 s8, s2, s5
	s_and_b32 s5, s8, -8
	s_sub_i32 s9, s2, s5
	s_cmp_gt_i32 s9, -1
	s_cbranch_scc0 .LBB0_1616
	s_lshl_b32 s5, s9, 5
	v_readlane_b32 s12, v247, 44
	v_readlane_b32 s13, v247, 45
	v_readlane_b32 s14, v247, 46
	v_readlane_b32 s15, v247, 47
	s_nop 4
	s_cbranch_execz .LBB0_1617
	s_branch .LBB0_1618

; template <class Epi, class Sched, bool ALIGN_EPI = false, bool SP2 = false, bool PAIR_ACC = false>
; __device__ __forceinline__ void gemm_phase(PG8_LAS unsigned char* lds, const Gemm g, const Sched& S, const Epi& E) {
;     int tid_ = threadIdx.x; asm volatile("" : "+v"(tid_));
;     const int tid = tid_, wid = __builtin_amdgcn_readfirstlane(tid >> 6), lane = tid & 63, wr = wid >> 2, wc = wid & 3, fr = lane & 15, fq = lane >> 4;
;     const int K = g.K, nt = K / BK;
;     unsigned voffA[2], voffB[2];
; #pragma unroll
;     for (int i = 0; i < 2; ++i) { int R, C; stage_rc(tid * 16 + i * 8192, R, C); const int Rb = Epi::PERM ? ((R & ~31) + perm32(R & 31)) : R;
;         voffA[i] = (unsigned)(R * K + C) * 2u; voffB[i] = (unsigned)(Rb * K + C) * 2u; }
;     const size_t kstep = (size_t)(BK * 2);
;     const size_t hstep = (size_t)HALF * K * 2;
;     const size_t tstep = 2 * hstep;
;     const unsigned ldsw = (unsigned)wid * 1024u;
;     const int aoff = lds_byte(wr * 64 + fr, fq * 8), boff = lds_byte(wc * 32 + fr, fq * 8);
;     ...
;     Unit cur, nxt; int ui = 0;
;     if (!S.next(0, cur)) return;
;     f32x4 acc[2][2][4][2];
; #pragma unroll
;     for (int a = 0; a < 2; ++a)
; #pragma unroll
;         for (int b = 0; b < 2; ++b)
; #pragma unroll
;             for (int m = 0; m < 4; ++m)
; #pragma unroll
;                 for (int n = 0; n < 2; ++n) acc[a][b][m][n] = (f32x4){0.f, 0.f, 0.f, 0.f};
;     bf16x8 At[4][2], B0[2][2], B1[2][2];
;     const char* cA = (const char*)g.A + (size_t)cur.pm * tstep + (size_t)(cur.pn / g.a_div) * g.a_sel; const char* cB = (const char*)g.Bt + (size_t)cur.pn * tstep;
;     S.a_ready(cur);
;     if constexpr (SP2) {
;         PG8_STAGE(PG8_SB(0, 0), cB, voffB); PG8_STAGE(PG8_SB(0, 1), cB + hstep, voffB); PG8_STAGE(PG8_SA(0, 0), cA, voffA); PG8_STAGE(PG8_SA(0, 1), cA + hstep, voffA);
;         if (wr == 1) PG8_BAR;
;         PG8_WAIT_V(2); PG8_BAR;
;         PG8_STAGE(PG8_SB(1, 0), cB + kstep, voffB); PG8_STAGE(PG8_SA(1, 0), cA + kstep, voffA); PG8_STAGE(PG8_SB(1, 1), cB + hstep + kstep, voffB);
;         PG8_WAIT_V(6); PG8_BAR;
; __device__ __forceinline__ void xcd_barrier(const XcdBarrier& b) {
;     ...
;             asm volatile("" ::: "memory");
;             xb_add(&bar[XB_XGEN(b.x)], 1u);
;             asm volatile("s_waitcnt vmcnt(0)" ::: "memory");
;         } else {
;             XB_SPIN(xb_ld(&bar[XB_XGEN(b.x)]) == gen, bar);
.LBB0_1727:
	s_or_b64 exec, exec, s[12:13]
.LBB0_1728:
	s_or_b64 exec, exec, s[6:7]
	v_readlane_b32 s4, v246, 16
	v_mov_b32_e32 v12, v0
	v_readlane_b32 s5, v246, 17
	s_waitcnt lgkmcnt(0)
	s_barrier
	s_andn2_b64 vcc, exec, s[4:5]
	v_readfirstlane_b32 s42, v12
	s_cbranch_vccnz .LBB0_1753
	v_lshlrev_b32_e32 v2, 4, v12
	v_add_u32_e32 v3, 0x2000, v2
	v_ashrrev_i32_e32 v4, 31, v3
	v_lshrrev_b32_e32 v4, 22, v4
	v_add_u32_e32 v4, v3, v4
	v_ashrrev_i32_e32 v10, 10, v4
	v_mul_i32_i24_e32 v4, 0x400, v10
	v_sub_u32_e32 v3, v3, v4
	v_lshrrev_b32_e32 v4, 4, v3
	v_bitop3_b32 v3, v4, v3, 32 bitop3:0x6c
	v_ashrrev_i32_e32 v4, 31, v3
	v_lshrrev_b32_e32 v4, 26, v4
	v_add_u32_e32 v4, v3, v4
	v_lshlrev_b32_e32 v5, 3, v10
	v_ashrrev_i32_e32 v11, 6, v4
	v_and_b32_e32 v5, -16, v5
	v_add_u32_e32 v5, v11, v5
	v_and_b32_e32 v6, 3, v11
	s_mov_b32 s8, 0x1fffe0
	v_lshrrev_b32_e32 v7, 2, v5
	v_lshlrev_b32_e32 v8, 1, v5
	v_and_b32_e32 v4, 0xc0, v4
	v_and_or_b32 v6, v5, s8, v6
	v_and_b32_e32 v7, 4, v7
	v_and_b32_e32 v8, 24, v8
	v_sub_u32_e32 v3, v3, v4
	v_mov_b32_e32 v4, 1
	v_or3_b32 v6, v6, v7, v8
	v_lshlrev_b32_e32 v7, 5, v10
	v_ashrrev_i16_sdwa v3, v4, sext(v3) dst_sel:DWORD dst_unused:UNUSED_PAD src0_sel:DWORD src1_sel:BYTE_0
	v_and_b32_e32 v7, 32, v7
	v_bfe_i32 v13, v3, 0, 16
	v_add_lshl_u32 v3, v7, v13, 1
	v_lshl_add_u32 v172, v6, 11, v3
	v_lshl_add_u32 v174, v5, 11, v3
	v_bfe_i32 v3, v12, 27, 1
	v_lshrrev_b32_e32 v3, 22, v3
	v_add_u32_e32 v3, v2, v3
	v_and_b32_e32 v3, 0xfffffc00, v3
	s_mov_b64 s[6:7], s[26:27]
	v_sub_u32_e32 v2, v2, v3
	v_lshrrev_b32_e32 v3, 4, v2
	v_ashrrev_i32_e32 v5, 31, v12
	v_bitop3_b32 v2, v3, v2, 32 bitop3:0x6c
	v_lshrrev_b32_e32 v5, 26, v5
	v_ashrrev_i32_e32 v3, 31, v2
	v_add_u32_e32 v5, v12, v5
	v_lshrrev_b32_e32 v3, 26, v3
	v_ashrrev_i32_e32 v15, 6, v5
	s_waitcnt lgkmcnt(0)
	s_add_u32 s4, s6, 0x4b00000
	v_add_u32_e32 v3, v2, v3
	v_lshlrev_b32_e32 v5, 3, v15
	s_addc_u32 s5, s7, 0
	v_ashrrev_i32_e32 v14, 6, v3
	v_and_b32_e32 v5, -16, v5
	s_add_u32 s24, s6, 0x1a80000
	v_add_u32_e32 v5, v14, v5
	v_and_b32_e32 v6, 3, v14
	s_addc_u32 s25, s7, 0
	v_and_or_b32 v6, v5, s8, v6
	s_lshr_b32 s8, s65, 29
	s_add_i32 s8, s2, s8
	s_ashr_i32 s30, s42, 6
	s_ashr_i32 s9, s8, 3
	s_and_b32 s8, s8, -8
	s_ashr_i32 s44, s42, 8
	s_lshl_b32 s34, s30, 10
	s_sub_i32 s8, s2, s8
	s_cmp_lt_i32 s8, 0
	s_movk_i32 s35, 0xb1
	s_cselect_b32 s10, s35, 0xb0
	s_mul_i32 s8, s10, s8
	s_add_i32 s8, s8, s9
	s_mul_hi_i32 s9, s8, 0x2e8ba2e9
	s_lshr_b32 s10, s9, 31
	s_ashr_i32 s9, s9, 5
	s_add_i32 s9, s9, s10
	s_lshl_b32 s10, s9, 3
	s_mulk_i32 s9, 0xb0
	s_sub_i32 s8, s8, s9
	s_sext_i32_i16 s9, s8
	s_bfe_u32 s9, s9, 0x3001c
	s_add_i32 s9, s8, s9
	s_sext_i32_i16 s11, s9
	s_and_b32 s9, s9, 0xfff8
	s_sub_i32 s8, s8, s9
	s_sext_i32_i16 s8, s8
	v_lshrrev_b32_e32 v7, 2, v5
	v_lshlrev_b32_e32 v8, 1, v5
	v_and_b32_e32 v3, 0xc0, v3
	s_lshr_b32 s38, s11, 3
	s_add_i32 s58, s10, s8
	v_and_b32_e32 v7, 4, v7
	v_and_b32_e32 v8, 24, v8
	v_sub_u32_e32 v2, v2, v3
	s_ashr_i32 s59, s58, 31
	s_bfe_i64 s[10:11], s[38:39], 0x100000
	v_or3_b32 v6, v6, v7, v8
	v_lshlrev_b32_e32 v7, 5, v15
	v_ashrrev_i16_sdwa v2, v4, sext(v2) dst_sel:DWORD dst_unused:UNUSED_PAD src0_sel:DWORD src1_sel:BYTE_0
	s_lshl_b64 s[8:9], s[58:59], 19
	s_lshl_b64 s[10:11], s[10:11], 19
	v_and_b32_e32 v7, 32, v7
	v_bfe_i32 v16, v2, 0, 16
	s_add_u32 s60, s24, s10
	v_add_lshl_u32 v2, v7, v16, 1
	s_addc_u32 s61, s25, s11
	s_add_i32 s36, s34, 0
	v_lshl_add_u32 v176, v6, 11, v2
	s_add_i32 m0, s36, 0x10000
	v_lshl_add_u32 v178, v5, 11, v2
	global_load_lds_dwordx4 v176, s[60:61]
	s_add_i32 m0, s36, 0x12000
	s_add_u32 s10, s60, 0x40000
	global_load_lds_dwordx4 v172, s[60:61]
	s_addc_u32 s11, s61, 0
	s_add_i32 m0, s36, 0x14000
	v_mov_b32_e32 v177, 0
	global_load_lds_dwordx4 v176, s[10:11]
	s_add_i32 m0, s36, 0x16000
	s_add_u32 s62, s4, s8
	s_addc_u32 s63, s5, s9
	s_add_i32 s37, s36, 0x2000
	global_load_lds_dwordx4 v172, s[10:11]
	s_mov_b32 m0, s36
	s_add_u32 s8, s62, 0x40000
	global_load_lds_dwordx4 v178, s[62:63]
	s_mov_b32 m0, s37
	s_addc_u32 s9, s63, 0
	s_add_i32 s49, s36, 0x4000
	global_load_lds_dwordx4 v174, s[62:63]
	s_mov_b32 m0, s49
	s_add_i32 s64, s36, 0x6000
	global_load_lds_dwordx4 v178, s[8:9]
	s_mov_b32 m0, s64
	v_mov_b32_e32 v173, v177
	global_load_lds_dwordx4 v174, s[8:9]
	v_readlane_b32 s8, v247, 36
	v_readlane_b32 s9, v247, 37
	v_readlane_b32 s10, v247, 38
	v_readlane_b32 s11, v247, 39
	s_nop 4
	v_mov_b32_e32 v179, v177
	v_mov_b32_e32 v175, v177
	s_cmp_eq_u32 s44, 1
	s_mov_b32 s66, 0
	v_lshl_add_u64 v[8:9], s[60:61], 0, v[176:177]
	v_lshl_add_u64 v[6:7], s[60:61], 0, v[172:173]
	v_lshl_add_u64 v[2:3], s[62:63], 0, v[178:179]
	s_cselect_b64 s[12:13], -1, 0
	s_cmp_lg_u32 s44, 1
	v_lshl_add_u64 v[4:5], s[62:63], 0, v[174:175]
	s_cbranch_scc1 .LBB0_1731
	s_barrier

;     __host__ __device__ void init(int M, int N, int G_, int c_) { base.init(M, N, G_, c_); G = G_; c = c_; }
;     __host__ __device__ void init(int M, int G_, int c_) { base.init(M, 1024, G_, c_); }
;     __host__ __device__ bool next(int i, Unit& u) const { Unit b; if (!base.next(i >> 1, b)) return false; u.pm = b.pm; u.pn = b.pn + 4 * (i & 1); return true; }
; __device__ __forceinline__ unsigned xb_ld(unsigned* p)              { return __hip_atomic_load(p, __ATOMIC_RELAXED, __HIP_MEMORY_SCOPE_AGENT); }
; __device__ __forceinline__ unsigned xb_add(unsigned* p, unsigned v) { return __hip_atomic_fetch_add(p, v, __ATOMIC_RELAXED, __HIP_MEMORY_SCOPE_AGENT); }
; #define XB_SPIN(cond, bar) do { unsigned _sp = 0; while (cond) { __builtin_amdgcn_s_sleep(1); \
;     if ((++_sp & 255u) == 0u) { if (xb_ld(&(bar)[XB_TMO])) break; if (_sp > XB_SPIN_CAP) { atomicAdd(&(bar)[XB_TMO], 1u); break; } } } } while (0)
; __device__ __forceinline__ void xcd_barrier(const XcdBarrier& b) {
;     ...
;             asm volatile("" ::: "memory");
;             xb_add(&bar[XB_XGEN(b.x)], 1u);
;             asm volatile("s_waitcnt vmcnt(0)" ::: "memory");
;         } else {
;             XB_SPIN(xb_ld(&bar[XB_XGEN(b.x)]) == gen, bar);
;             asm volatile("" ::: "memory");
;             asm volatile("s_waitcnt vmcnt(0)" ::: "memory");
;         }
;     }
;     __syncthreads();
; __global__ void __launch_bounds__(512, 2) fwd_mega(Args a) {
;     ...
;             pg8::Gemm g{WSP(WS_ACT), WSP(l == 0 ? WS_WD : WS_WD1), M, D, FF, 1 << 20, 0}; pg8::StaticOrder S; S.init(M, D, G, bx);
;             {
;                 const float* cw = INF(18) + (size_t)l * 3 * FF; const float* cbp = INF(19) + (size_t)l * FF;
;                 const float* RA = (const float*)(a.ws + WS_RAWA); const float* RU = (const float*)(a.ws + WS_RAWU); const float* TA = (const float*)(a.ws + WS_TAILA);
;                 pg8::Unit fu;
;                 for (int i = 0; S.next(i, fu); ++i) {
;                     if ((fu.pm & 15) == 0) continue;
;                     for (int idx = threadIdx.x; idx < 2 * FF; idx += 512) {
;                         const int j = idx / FF, f = idx % FF; const size_t cur = (size_t)fu.pm * 2 * FF, prv = (size_t)(fu.pm - 1) * 2 * FF;
;                         const float a2 = RA[cur + j * FF + f], a1 = (j == 0) ? TA[prv + FF + f] : RA[cur + f], a0 = (j == 0) ? TA[prv + f] : TA[prv + FF + f];
.LBB0_1804:
	s_or_b64 exec, exec, s[12:13]
.LBB0_1805:
	s_or_b64 exec, exec, s[6:7]
	s_waitcnt lgkmcnt(0)
	s_barrier
	v_readlane_b32 s4, v247, 36
	v_readlane_b32 s5, v247, 37
	v_readlane_b32 s6, v247, 38
	v_readlane_b32 s7, v247, 39
	v_readlane_b32 s12, v247, 46
	v_readlane_b32 s13, v247, 47
	s_nop 4
	s_mov_b32 s24, 0
	v_mov_b64_e32 v[2:3], 0x100
	v_mov_b64_e32 v[4:5], 0xff
	s_waitcnt lgkmcnt(0)
	s_add_u32 s8, s4, 0x8400
	s_addc_u32 s9, s5, 0
	s_add_u32 s10, s6, 0x2c00
	s_addc_u32 s11, s7, 0
	s_add_u32 s14, s12, 0x200000
	s_addc_u32 s15, s13, 0
	s_add_u32 s18, s12, 0x380000
	s_addc_u32 s19, s13, 0
	s_add_u32 s4, s12, 0x500000
	s_addc_u32 s5, s13, 0
	s_add_u32 s16, s12, 0x6b00000
	s_addc_u32 s17, s13, 0
	s_movk_i32 s25, 0x1600
	s_movk_i32 s26, 0xaff
	v_mov_b32_e32 v7, 0
	s_movk_i32 s27, 0x2000
	s_movk_i32 s28, 0x5000
	s_movk_i32 s29, 0x7fff
	s_movk_i32 s30, 0x13ff
	v_mov_b32_e32 v10, 0xb00
	v_mov_b64_e32 v[8:9], s[16:17]
	s_branch .LBB0_1808
